# gla_prep: q/k column loads use 4 base addresses + immediate row offsets instead of 16 recomputed 64-bit addresses
# speedup vs baseline: 1.0071x; 1.0013x over previous
.LBB0_387:
	s_or_b64 exec, exec, s[54:55]
	s_lshl_b32 s54, s71, 6
	s_and_b32 s54, s54, 0x180
	v_or_b32_e32 v41, s1, v41
	v_or_b32_e32 v48, s54, v71
	v_lshl_or_b32 v64, v41, 9, v48
	v_lshl_add_u64 v[42:43], v[64:65], 2, s[60:61]
	v_add_co_u32_e32 v44, vcc, 0x1000, v42
	s_movk_i32 s55, 0x2000
	s_nop 0
	v_addc_co_u32_e32 v45, vcc, 0, v43, vcc
	global_load_dword v91, v[42:43], off
	global_load_dword v90, v[42:43], off offset:2048
	global_load_dword v92, v[44:45], off
	global_load_dword v94, v[44:45], off offset:2048
	v_add_co_u32_e32 v44, vcc, s55, v42
	s_movk_i32 s55, 0x3000
	s_nop 0
	v_addc_co_u32_e32 v45, vcc, 0, v43, vcc
	v_add_co_u32_e32 v46, vcc, s55, v42
	s_movk_i32 s55, 0x5000
	s_nop 0
	v_addc_co_u32_e32 v47, vcc, 0, v43, vcc
	global_load_dword v96, v[46:47], off offset:-4096
	global_load_dword v95, v[44:45], off offset:2048
	global_load_dword v98, v[46:47], off
	global_load_dword v99, v[46:47], off offset:2048
	v_add_co_u32_e32 v44, vcc, s33, v42
	v_add3_u32 v40, s83, v72, v40
	s_nop 0
	v_addc_co_u32_e32 v45, vcc, 0, v43, vcc
	v_add_co_u32_e32 v46, vcc, s55, v42
	s_movk_i32 s55, 0x6000
	s_nop 0
	v_addc_co_u32_e32 v47, vcc, 0, v43, vcc
	global_load_dword v101, v[46:47], off offset:-4096
	global_load_dword v100, v[44:45], off offset:2048
	global_load_dword v102, v[46:47], off
	global_load_dword v103, v[46:47], off offset:2048
	v_add_co_u32_e32 v44, vcc, s55, v42
	s_movk_i32 s55, 0x7000
	s_nop 0
	v_addc_co_u32_e32 v45, vcc, 0, v43, vcc
	v_add_co_u32_e32 v42, vcc, s55, v42
	s_lshl_b32 s55, s70, 9
	s_or_b32 s55, s55, s65
	s_or_b32 s54, s55, s54
	v_addc_co_u32_e32 v43, vcc, 0, v43, vcc
	v_or_b32_e32 v64, s54, v71
	global_load_dword v104, v[42:43], off offset:-4096
	global_load_dword v106, v[44:45], off offset:2048
	global_load_dword v108, v[42:43], off
	global_load_dword v110, v[42:43], off offset:2048
	v_lshl_add_u64 v[42:43], v[64:65], 2, s[62:63]
	v_ashrrev_i32_e32 v41, 31, v40
	global_load_dword v64, v[42:43], off
	v_lshlrev_b64 v[42:43], 10, v[40:41]
	v_lshlrev_b32_e32 v46, 1, v48
	v_or_b32_e32 v42, v42, v46
	v_lshl_add_u64 v[44:45], s[58:59], 0, v[42:43]
	v_lshl_add_u64 v[42:43], s[92:93], 0, v[42:43]
	s_mov_b32 s98, 0x1000
	s_mov_b32 s99, 0
	global_load_ushort v114, v[44:45], off
	global_load_ushort v240, v[42:43], off
	global_load_ushort v115, v[44:45], off offset:1024
	global_load_ushort v241, v[42:43], off offset:1024
	global_load_ushort v117, v[44:45], off offset:2048
	global_load_ushort v242, v[42:43], off offset:2048
	global_load_ushort v120, v[44:45], off offset:3072
	global_load_ushort v243, v[42:43], off offset:3072
	v_lshl_add_u64 v[44:45], v[44:45], 0, s[98:99]
	v_lshl_add_u64 v[42:43], v[42:43], 0, s[98:99]
	global_load_ushort v123, v[44:45], off
	global_load_ushort v244, v[42:43], off
	global_load_ushort v125, v[44:45], off offset:1024
	global_load_ushort v245, v[42:43], off offset:1024
	global_load_ushort v126, v[44:45], off offset:2048
	global_load_ushort v246, v[42:43], off offset:2048
	global_load_ushort v128, v[44:45], off offset:3072
	global_load_ushort v247, v[42:43], off offset:3072
	v_lshl_add_u64 v[44:45], v[44:45], 0, s[98:99]
	v_lshl_add_u64 v[42:43], v[42:43], 0, s[98:99]
	global_load_ushort v129, v[44:45], off
	global_load_ushort v248, v[42:43], off
	global_load_ushort v131, v[44:45], off offset:1024
	global_load_ushort v249, v[42:43], off offset:1024
	global_load_ushort v132, v[44:45], off offset:2048
	global_load_ushort v250, v[42:43], off offset:2048
	global_load_ushort v133, v[44:45], off offset:3072
	global_load_ushort v251, v[42:43], off offset:3072
	v_lshl_add_u64 v[44:45], v[44:45], 0, s[98:99]
	v_lshl_add_u64 v[42:43], v[42:43], 0, s[98:99]
	global_load_ushort v135, v[44:45], off
	global_load_ushort v252, v[42:43], off
	global_load_ushort v137, v[44:45], off offset:1024
	global_load_ushort v253, v[42:43], off offset:1024
	global_load_ushort v138, v[44:45], off offset:2048
	global_load_ushort v254, v[42:43], off offset:2048
	global_load_ushort v139, v[44:45], off offset:3072
	global_load_ushort v255, v[42:43], off offset:3072
	s_branch .LBB0_389
